# gdn_prep step 1b: quad sums for the q/k L2 norms by DPP adds instead of ds_bpermute
# baseline (speedup 1.0000x reference)
; #define LAS __attribute__((address_space(3)))
; __device__ __forceinline__ float siluf(float x) { return x * __builtin_amdgcn_rcpf(1.0f + __expf(-x)); }
; __device__ __forceinline__ void unpack8(v4u w, float (&f)[8]) { f[0] = bflo(w.x); f[1] = bfhi(w.x); f[2] = bflo(w.y); f[3] = bfhi(w.y); f[4] = bflo(w.z); f[5] = bfhi(w.z); f[6] = bflo(w.w); f[7] = bfhi(w.w); }
; __device__ __forceinline__ void gdn_prep_all(const Params& P, LAS unsigned char* lds, int tid, int lane, int wave, int G) {
;     ...
;         for (int k = 0; k < 7; ++k) { const int q = tih + 256 * k; if (q < 1608) *(LAS v4u*)(hb + RAW_OFF + q * 16) = pre[k]; }
;         __syncthreads();
;     ...
;         if (!(P.flags & 256))
;     ...
;         {
;             const int t = t1;
; #pragma unroll
;             for (int p = 0; p < 3; ++p) {
;                 float acc[16];
; #pragma unroll
;                 for (int i = 0; i < 16; ++i) acc[i] = 0.f;
; #pragma unroll
;                 for (int j = 0; j < 4; ++j) {
;                     float rw[16];
;                     { const LAS v4u* rp = (const LAS v4u*)(hb + RAW_OFF + (t + j) * 384 + (p * 64 + 16 * cg) * 2);
;                       float f0[8], f1[8]; unpack8(rp[0], f0); unpack8(rp[1], f1);
; #pragma unroll
;                       for (int i = 0; i < 8; ++i) { rw[i] = f0[i]; rw[8 + i] = f1[i]; } }
;                     const LAS float* cwj = (const LAS float*)(hb + CW_OFF) + j * 192 + p * 64 + 16 * cg;
; #pragma unroll
;                     for (int i4 = 0; i4 < 4; ++i4) { const f32x4 w = ((const LAS f32x4*)cwj)[i4];
;                         acc[4 * i4] += rw[4 * i4] * w[0]; acc[4 * i4 + 1] += rw[4 * i4 + 1] * w[1]; acc[4 * i4 + 2] += rw[4 * i4 + 2] * w[2]; acc[4 * i4 + 3] += rw[4 * i4 + 3] * w[3]; }
;                 }
;                 float ss = 0.f;
; #pragma unroll
;                 for (int i = 0; i < 16; ++i) { acc[i] = siluf(acc[i]); ss += acc[i] * acc[i]; }
.LBB0_351:
	s_waitcnt vmcnt(0)
	ds_write_b128 v156, v[2:5] offset:27648
	ds_write_b128 v157, v[6:9] offset:27648
	ds_write_b128 v158, v[10:13] offset:27648
	ds_write_b128 v159, v[14:17] offset:27648
	ds_write_b128 v160, v[18:21] offset:27648
	ds_write_b128 v161, v[22:25] offset:27648
	s_and_saveexec_b64 s[14:15], s[34:35]
	ds_write_b128 v162, v[26:29] offset:27648
	s_or_b64 exec, exec, s[14:15]
	s_waitcnt lgkmcnt(0)
	s_barrier
	ds_read_b128 v[36:39], v163 offset:27648
	ds_read_b128 v[66:69], v163 offset:27664
	ds_read_b128 v[32:35], v164 offset:59648
	ds_read_b128 v[70:73], v164 offset:59664
	ds_read_b128 v[74:77], v164 offset:59680
	ds_read_b128 v[60:63], v164 offset:59696
	ds_read_b128 v[44:47], v163 offset:28032
	ds_read_b128 v[188:191], v163 offset:28048
	ds_read_b128 v[40:43], v164 offset:60416
	ds_read_b128 v[192:195], v164 offset:60432
	ds_read_b128 v[196:199], v164 offset:60448
	ds_read_b128 v[200:203], v164 offset:60464
	ds_read_b128 v[48:51], v163 offset:28416
	ds_read_b128 v[204:207], v163 offset:28432
	ds_read_b128 v[208:211], v164 offset:61216
	ds_read_b128 v[212:215], v164 offset:61232
	ds_read_b128 v[52:55], v163 offset:28800
	ds_read_b128 v[216:219], v163 offset:28816
	ds_read_b128 v[220:223], v164 offset:61984
	ds_read_b128 v[224:227], v164 offset:62000
	s_waitcnt lgkmcnt(14)
	v_lshlrev_b32_e32 v56, 16, v69
	v_and_b32_e32 v57, 0xffff0000, v69
	v_pk_fma_f32 v[56:57], v[62:63], v[56:57], 0 op_sel_hi:[1,1,0]
	s_waitcnt lgkmcnt(12)
	v_lshlrev_b32_e32 v58, 16, v191
	v_and_b32_e32 v59, 0xffff0000, v191
	s_waitcnt lgkmcnt(8)
	v_pk_fma_f32 v[56:57], v[202:203], v[58:59], v[56:57]
	s_waitcnt lgkmcnt(6)
	v_lshlrev_b32_e32 v58, 16, v207
	v_and_b32_e32 v59, 0xffff0000, v207
	v_lshlrev_b32_e32 v202, 16, v68
	v_and_b32_e32 v203, 0xffff0000, v68
	s_waitcnt lgkmcnt(4)
	v_pk_fma_f32 v[56:57], v[214:215], v[58:59], v[56:57]
	s_waitcnt lgkmcnt(2)
	v_lshlrev_b32_e32 v58, 16, v219
	v_and_b32_e32 v59, 0xffff0000, v219
	v_pk_fma_f32 v[60:61], v[60:61], v[202:203], 0 op_sel_hi:[1,1,0]
	v_lshlrev_b32_e32 v68, 16, v190
	v_and_b32_e32 v69, 0xffff0000, v190
	s_waitcnt lgkmcnt(0)
	v_pk_fma_f32 v[62:63], v[226:227], v[58:59], v[56:57]
	v_pk_fma_f32 v[60:61], v[200:201], v[68:69], v[60:61]
	v_lshlrev_b32_e32 v68, 16, v206
	v_and_b32_e32 v69, 0xffff0000, v206
	v_mul_f32_e32 v31, 0xbfb8aa3b, v62
	v_pk_fma_f32 v[60:61], v[212:213], v[68:69], v[60:61]
	v_lshlrev_b32_e32 v68, 16, v218
	v_and_b32_e32 v69, 0xffff0000, v218
	v_exp_f32_e32 v31, v31
	v_mul_f32_e32 v56, 0xbfb8aa3b, v63
	v_pk_fma_f32 v[68:69], v[224:225], v[68:69], v[60:61]
	v_exp_f32_e32 v65, v56
	v_mul_f32_e32 v60, 0xbfb8aa3b, v68
	v_exp_f32_e32 v60, v60
	v_mul_f32_e32 v61, 0xbfb8aa3b, v69
	v_exp_f32_e32 v61, v61
	v_add_f32_e32 v31, 1.0, v31
	v_rcp_f32_e32 v64, v31
	v_add_f32_e32 v31, 1.0, v65
	v_rcp_f32_e32 v65, v31
	v_add_f32_e32 v31, 1.0, v60
	v_rcp_f32_e32 v190, v31
	v_add_f32_e32 v31, 1.0, v61
	v_rcp_f32_e32 v191, v31
	v_pk_mul_f32 v[60:61], v[62:63], v[64:65]
	ds_read_b128 v[56:59], v164 offset:61184
	ds_read_b128 v[226:229], v164 offset:61200
	ds_read_b128 v[200:203], v164 offset:61952
	ds_read_b128 v[212:215], v164 offset:61968
	v_pk_mul_f32 v[62:63], v[68:69], v[190:191]
	v_lshlrev_b32_e32 v68, 16, v67
	v_and_b32_e32 v69, 0xffff0000, v67
	v_pk_fma_f32 v[68:69], v[76:77], v[68:69], 0 op_sel_hi:[1,1,0]
	v_lshlrev_b32_e32 v76, 16, v189
	v_and_b32_e32 v77, 0xffff0000, v189
	v_pk_fma_f32 v[68:69], v[198:199], v[76:77], v[68:69]
	v_lshlrev_b32_e32 v76, 16, v205
	v_and_b32_e32 v77, 0xffff0000, v205
	v_pk_fma_f32 v[68:69], v[210:211], v[76:77], v[68:69]
	v_lshlrev_b32_e32 v76, 16, v217
	v_and_b32_e32 v77, 0xffff0000, v217
	v_pk_fma_f32 v[68:69], v[222:223], v[76:77], v[68:69]
	v_lshlrev_b32_e32 v198, 16, v66
	v_mul_f32_e32 v31, 0xbfb8aa3b, v68
	v_exp_f32_e32 v31, v31
	v_mul_f32_e32 v67, 0xbfb8aa3b, v69
	v_exp_f32_e32 v67, v67
	v_and_b32_e32 v199, 0xffff0000, v66
	v_add_f32_e32 v31, 1.0, v31
	v_rcp_f32_e32 v190, v31
	v_add_f32_e32 v31, 1.0, v67
	v_pk_fma_f32 v[66:67], v[74:75], v[198:199], 0 op_sel_hi:[1,1,0]
	v_lshlrev_b32_e32 v74, 16, v188
	v_and_b32_e32 v75, 0xffff0000, v188
	v_pk_fma_f32 v[66:67], v[196:197], v[74:75], v[66:67]
	v_lshlrev_b32_e32 v74, 16, v204
	v_and_b32_e32 v75, 0xffff0000, v204
	v_lshlrev_b32_e32 v188, 16, v39
	v_and_b32_e32 v189, 0xffff0000, v39
	v_pk_fma_f32 v[66:67], v[208:209], v[74:75], v[66:67]
	v_lshlrev_b32_e32 v74, 16, v216
	v_and_b32_e32 v75, 0xffff0000, v216
	v_pk_fma_f32 v[72:73], v[72:73], v[188:189], 0 op_sel_hi:[1,1,0]
	v_lshlrev_b32_e32 v188, 16, v47
	v_and_b32_e32 v189, 0xffff0000, v47
	v_pk_fma_f32 v[66:67], v[220:221], v[74:75], v[66:67]
	v_pk_fma_f32 v[72:73], v[194:195], v[188:189], v[72:73]
	v_lshlrev_b32_e32 v188, 16, v51
	v_and_b32_e32 v189, 0xffff0000, v51
	v_rcp_f32_e32 v191, v31
	v_mul_f32_e32 v31, 0xbfb8aa3b, v66
	s_waitcnt lgkmcnt(2)
	v_pk_fma_f32 v[72:73], v[228:229], v[188:189], v[72:73]
	v_lshlrev_b32_e32 v188, 16, v55
	v_and_b32_e32 v189, 0xffff0000, v55
	v_exp_f32_e32 v31, v31
	v_mul_f32_e32 v74, 0xbfb8aa3b, v67
	s_waitcnt lgkmcnt(0)
; #define LAS __attribute__((address_space(3)))
; __device__ __forceinline__ unsigned pk2(float lo, float hi) { return pg8::cvt_pk_bf16_v(lo, hi); }
; __device__ __forceinline__ float siluf(float x) { return x * __builtin_amdgcn_rcpf(1.0f + __expf(-x)); }
; __device__ __forceinline__ void gdn_prep_all(const Params& P, LAS unsigned char* lds, int tid, int lane, int wave, int G) {
;     ...
;                 float ss = 0.f;
; #pragma unroll
;                 for (int i = 0; i < 16; ++i) { acc[i] = siluf(acc[i]); ss += acc[i] * acc[i]; }
;                 ss += __shfl_xor(ss, 1); ss += __shfl_xor(ss, 2);
;                 float scale = 1.f;
;                 if (p == 0) scale = 0.125f * __builtin_amdgcn_rsqf(ss + 1e-6f); else if (p == 1) scale = __builtin_amdgcn_rsqf(ss + 1e-6f);
;                 if (t >= I.L) scale = 0.f;
;                 v4u o0, o1;
;                 o0.x = pk2(acc[0] * scale, acc[1] * scale); o0.y = pk2(acc[2] * scale, acc[3] * scale); o0.z = pk2(acc[4] * scale, acc[5] * scale); o0.w = pk2(acc[6] * scale, acc[7] * scale);
;                 o1.x = pk2(acc[8] * scale, acc[9] * scale); o1.y = pk2(acc[10] * scale, acc[11] * scale); o1.z = pk2(acc[12] * scale, acc[13] * scale); o1.w = pk2(acc[14] * scale, acc[15] * scale);
;                 LAS v4u* dst = (LAS v4u*)(hb + p * 9216 + t * 144 + cg * 32);
;                 dst[0] = o0; dst[1] = o1;
	v_pk_fma_f32 v[72:73], v[214:215], v[188:189], v[72:73]
	v_exp_f32_e32 v75, v74
	v_mul_f32_e32 v39, 0xbfb8aa3b, v72
	v_exp_f32_e32 v39, v39
	v_mul_f32_e32 v47, 0xbfb8aa3b, v73
	v_exp_f32_e32 v47, v47
	v_add_f32_e32 v31, 1.0, v31
	v_rcp_f32_e32 v74, v31
	v_add_f32_e32 v31, 1.0, v75
	v_rcp_f32_e32 v75, v31
	v_add_f32_e32 v31, 1.0, v39
	v_rcp_f32_e32 v188, v31
	v_add_f32_e32 v31, 1.0, v47
	v_rcp_f32_e32 v189, v31
	v_and_b32_e32 v47, 0xffff0000, v50
	v_and_b32_e32 v55, 0xffff0000, v37
	v_pk_mul_f32 v[66:67], v[66:67], v[74:75]
	v_pk_mul_f32 v[72:73], v[72:73], v[188:189]
	v_lshlrev_b32_e32 v188, 16, v38
	v_and_b32_e32 v189, 0xffff0000, v38
	v_pk_fma_f32 v[38:39], v[70:71], v[188:189], 0 op_sel_hi:[1,1,0]
	v_lshlrev_b32_e32 v70, 16, v46
	v_and_b32_e32 v71, 0xffff0000, v46
	v_pk_fma_f32 v[38:39], v[192:193], v[70:71], v[38:39]
	v_lshlrev_b32_e32 v46, 16, v50
	v_pk_fma_f32 v[38:39], v[226:227], v[46:47], v[38:39]
	v_lshlrev_b32_e32 v46, 16, v54
	v_and_b32_e32 v47, 0xffff0000, v54
	v_pk_fma_f32 v[38:39], v[212:213], v[46:47], v[38:39]
	v_lshlrev_b32_e32 v54, 16, v37
	v_mul_f32_e32 v31, 0xbfb8aa3b, v38
	v_exp_f32_e32 v31, v31
	v_mul_f32_e32 v46, 0xbfb8aa3b, v39
	v_exp_f32_e32 v51, v46
	v_pk_fma_f32 v[34:35], v[34:35], v[54:55], 0 op_sel_hi:[1,1,0]
	v_lshlrev_b32_e32 v54, 16, v45
	v_and_b32_e32 v55, 0xffff0000, v45
	v_pk_fma_f32 v[34:35], v[42:43], v[54:55], v[34:35]
	v_lshlrev_b32_e32 v42, 16, v49
	v_and_b32_e32 v43, 0xffff0000, v49
	v_add_f32_e32 v31, 1.0, v31
	v_pk_fma_f32 v[34:35], v[58:59], v[42:43], v[34:35]
	v_lshlrev_b32_e32 v42, 16, v53
	v_and_b32_e32 v43, 0xffff0000, v53
	v_rcp_f32_e32 v50, v31
	v_add_f32_e32 v31, 1.0, v51
	v_pk_fma_f32 v[34:35], v[202:203], v[42:43], v[34:35]
	v_rcp_f32_e32 v51, v31
	v_mul_f32_e32 v31, 0xbfb8aa3b, v34
	v_exp_f32_e32 v31, v31
	v_mul_f32_e32 v37, 0xbfb8aa3b, v35
	v_exp_f32_e32 v37, v37
	v_pk_mul_f32 v[38:39], v[38:39], v[50:51]
	v_add_f32_e32 v31, 1.0, v31
	v_lshlrev_b32_e32 v50, 16, v36
	v_and_b32_e32 v51, 0xffff0000, v36
	v_rcp_f32_e32 v42, v31
	v_add_f32_e32 v31, 1.0, v37
	v_pk_fma_f32 v[32:33], v[32:33], v[50:51], 0 op_sel_hi:[1,1,0]
	v_lshlrev_b32_e32 v36, 16, v44
	v_and_b32_e32 v37, 0xffff0000, v44
	v_pk_fma_f32 v[32:33], v[40:41], v[36:37], v[32:33]
	v_lshlrev_b32_e32 v36, 16, v48
	v_and_b32_e32 v37, 0xffff0000, v48
	v_pk_fma_f32 v[32:33], v[56:57], v[36:37], v[32:33]
	v_lshlrev_b32_e32 v36, 16, v52
	v_and_b32_e32 v37, 0xffff0000, v52
	v_pk_fma_f32 v[32:33], v[200:201], v[36:37], v[32:33]
	v_rcp_f32_e32 v43, v31
	v_mul_f32_e32 v36, 0xbfb8aa3b, v32
	v_exp_f32_e32 v36, v36
	v_mul_f32_e32 v37, 0xbfb8aa3b, v33
	v_exp_f32_e32 v37, v37
	v_pk_mul_f32 v[34:35], v[34:35], v[42:43]
	v_add_f32_e32 v31, 1.0, v36
	v_rcp_f32_e32 v36, v31
	v_add_f32_e32 v31, 1.0, v37
	v_rcp_f32_e32 v37, v31
	v_pk_mul_f32 v[42:43], v[34:35], v[34:35]
	v_pk_mul_f32 v[40:41], v[38:39], v[38:39]
	v_pk_mul_f32 v[46:47], v[72:73], v[72:73]
	v_pk_mul_f32 v[32:33], v[32:33], v[36:37]
	v_pk_mul_f32 v[74:75], v[66:67], v[66:67]
	v_pk_mul_f32 v[36:37], v[32:33], v[32:33]
	v_pk_mul_f32 v[68:69], v[68:69], v[190:191]
	v_add_f32_e32 v31, v36, v37
	v_add_f32_e32 v31, v42, v31
	v_add_f32_e32 v31, v43, v31
	v_add_f32_e32 v31, v40, v31
	v_add_f32_e32 v31, v41, v31
	v_add_f32_e32 v31, v46, v31
	v_add_f32_e32 v31, v47, v31
	v_add_f32_e32 v31, v74, v31
	v_pk_mul_f32 v[190:191], v[68:69], v[68:69]
	v_add_f32_e32 v31, v75, v31
	v_add_f32_e32 v31, v190, v31
	v_pk_mul_f32 v[76:77], v[62:63], v[62:63]
	v_add_f32_e32 v31, v191, v31
	v_add_f32_e32 v31, v76, v31
	v_pk_mul_f32 v[64:65], v[60:61], v[60:61]
	v_add_f32_e32 v31, v77, v31
	v_add_f32_e32 v31, v64, v31
	v_add_f32_e32 v31, v65, v31
	s_ashr_i32 s16, s2, 2
	s_cmpk_gt_i32 s16, 0x3ff
	s_cselect_b32 s12, 16, 64
	v_cmp_gt_u32_e32 vcc, s12, v109
	v_add_f32_dpp v31, v31, v31 quad_perm:[1,0,3,2] row_mask:0xf bank_mask:0xf
	s_add_i32 s2, s2, s3
	s_cmpk_lt_i32 s2, 0x1040
	s_cselect_b64 s[92:93], -1, 0
	s_cmpk_gt_i32 s2, 0x103f
	v_add_f32_dpp v31, v31, v31 quad_perm:[2,3,0,1] row_mask:0xf bank_mask:0xf
	v_add_f32_e32 v31, 0x358637bd, v31
	v_rsq_f32_e32 v31, v31
	s_cselect_b64 s[90:91], -1, 0
	v_mul_f32_e32 v31, 0x3e000000, v31
	v_cndmask_b32_e32 v40, 0, v31, vcc
	v_pk_mul_f32 v[32:33], v[32:33], v[40:41] op_sel_hi:[1,0]
	v_pk_mul_f32 v[34:35], v[34:35], v[40:41] op_sel_hi:[1,0]
	v_cvt_pk_bf16_f32 v32, v32, v33
	v_cvt_pk_bf16_f32 v33, v34, v35
	v_pk_mul_f32 v[34:35], v[38:39], v[40:41] op_sel_hi:[1,0]
	v_pk_mul_f32 v[36:37], v[72:73], v[40:41] op_sel_hi:[1,0]
	v_cvt_pk_bf16_f32 v34, v34, v35
	v_cvt_pk_bf16_f32 v35, v36, v37
	v_pk_mul_f32 v[36:37], v[66:67], v[40:41] op_sel_hi:[1,0]
	v_pk_mul_f32 v[38:39], v[68:69], v[40:41] op_sel_hi:[1,0]
	v_cvt_pk_bf16_f32 v36, v36, v37
	v_cvt_pk_bf16_f32 v37, v38, v39
	v_pk_mul_f32 v[38:39], v[62:63], v[40:41] op_sel_hi:[1,0]
	v_pk_mul_f32 v[40:41], v[60:61], v[40:41] op_sel_hi:[1,0]
	v_cvt_pk_bf16_f32 v38, v38, v39
	v_cvt_pk_bf16_f32 v39, v40, v41
	ds_write_b128 v165, v[32:35]
	ds_write_b128 v165, v[36:39] offset:16
	ds_read_b128 v[36:39], v163 offset:27776
	ds_read_b128 v[66:69], v163 offset:27792
	ds_read_b128 v[32:35], v164 offset:59904
	ds_read_b128 v[70:73], v164 offset:59920
	ds_read_b128 v[74:77], v164 offset:59936
	ds_read_b128 v[60:63], v164 offset:59952
	ds_read_b128 v[44:47], v163 offset:28160
	ds_read_b128 v[188:191], v163 offset:28176
	ds_read_b128 v[40:43], v164 offset:60672
	ds_read_b128 v[192:195], v164 offset:60688
	ds_read_b128 v[196:199], v164 offset:60704
	ds_read_b128 v[200:203], v164 offset:60720
	ds_read_b128 v[48:51], v163 offset:28544
	ds_read_b128 v[204:207], v163 offset:28560
	ds_read_b128 v[208:211], v164 offset:61472
	ds_read_b128 v[212:215], v164 offset:61488
	ds_read_b128 v[52:55], v163 offset:28928
	ds_read_b128 v[216:219], v163 offset:28944
	ds_read_b128 v[220:223], v164 offset:62240
	ds_read_b128 v[224:227], v164 offset:62256
	s_waitcnt lgkmcnt(14)
; #define LAS __attribute__((address_space(3)))
; __device__ __forceinline__ float siluf(float x) { return x * __builtin_amdgcn_rcpf(1.0f + __expf(-x)); }
; __device__ __forceinline__ void unpack8(v4u w, float (&f)[8]) { f[0] = bflo(w.x); f[1] = bfhi(w.x); f[2] = bflo(w.y); f[3] = bfhi(w.y); f[4] = bflo(w.z); f[5] = bfhi(w.z); f[6] = bflo(w.w); f[7] = bfhi(w.w); }
; __device__ __forceinline__ void gdn_prep_all(const Params& P, LAS unsigned char* lds, int tid, int lane, int wave, int G) {
;     ...
;                 for (int j = 0; j < 4; ++j) {
;                     float rw[16];
;                     { const LAS v4u* rp = (const LAS v4u*)(hb + RAW_OFF + (t + j) * 384 + (p * 64 + 16 * cg) * 2);
;                       float f0[8], f1[8]; unpack8(rp[0], f0); unpack8(rp[1], f1);
; #pragma unroll
;                       for (int i = 0; i < 8; ++i) { rw[i] = f0[i]; rw[8 + i] = f1[i]; } }
;                     const LAS float* cwj = (const LAS float*)(hb + CW_OFF) + j * 192 + p * 64 + 16 * cg;
; #pragma unroll
;                     for (int i4 = 0; i4 < 4; ++i4) { const f32x4 w = ((const LAS f32x4*)cwj)[i4];
;                         acc[4 * i4] += rw[4 * i4] * w[0]; acc[4 * i4 + 1] += rw[4 * i4 + 1] * w[1]; acc[4 * i4 + 2] += rw[4 * i4 + 2] * w[2]; acc[4 * i4 + 3] += rw[4 * i4 + 3] * w[3]; }
;                 }
;                 float ss = 0.f;
; #pragma unroll
;                 for (int i = 0; i < 16; ++i) { acc[i] = siluf(acc[i]); ss += acc[i] * acc[i]; }
	v_lshlrev_b32_e32 v56, 16, v69
	v_and_b32_e32 v57, 0xffff0000, v69
	v_pk_fma_f32 v[56:57], v[62:63], v[56:57], 0 op_sel_hi:[1,1,0]
	s_waitcnt lgkmcnt(12)
	v_lshlrev_b32_e32 v58, 16, v191
	v_and_b32_e32 v59, 0xffff0000, v191
	s_waitcnt lgkmcnt(8)
	v_pk_fma_f32 v[56:57], v[202:203], v[58:59], v[56:57]
	s_waitcnt lgkmcnt(6)
	v_lshlrev_b32_e32 v58, 16, v207
	v_and_b32_e32 v59, 0xffff0000, v207
	v_lshlrev_b32_e32 v202, 16, v68
	v_and_b32_e32 v203, 0xffff0000, v68
	s_waitcnt lgkmcnt(4)
	v_pk_fma_f32 v[56:57], v[214:215], v[58:59], v[56:57]
	s_waitcnt lgkmcnt(2)
	v_lshlrev_b32_e32 v58, 16, v219
	v_and_b32_e32 v59, 0xffff0000, v219
	v_pk_fma_f32 v[60:61], v[60:61], v[202:203], 0 op_sel_hi:[1,1,0]
	v_lshlrev_b32_e32 v68, 16, v190
	v_and_b32_e32 v69, 0xffff0000, v190
	s_waitcnt lgkmcnt(0)
	v_pk_fma_f32 v[62:63], v[226:227], v[58:59], v[56:57]
	v_pk_fma_f32 v[60:61], v[200:201], v[68:69], v[60:61]
	v_lshlrev_b32_e32 v68, 16, v206
	v_and_b32_e32 v69, 0xffff0000, v206
	v_mul_f32_e32 v31, 0xbfb8aa3b, v62
	v_pk_fma_f32 v[60:61], v[212:213], v[68:69], v[60:61]
	v_lshlrev_b32_e32 v68, 16, v218
	v_and_b32_e32 v69, 0xffff0000, v218
	v_exp_f32_e32 v31, v31
	v_mul_f32_e32 v56, 0xbfb8aa3b, v63
	v_pk_fma_f32 v[68:69], v[224:225], v[68:69], v[60:61]
	v_exp_f32_e32 v65, v56
	v_mul_f32_e32 v60, 0xbfb8aa3b, v68
	v_exp_f32_e32 v60, v60
	v_mul_f32_e32 v61, 0xbfb8aa3b, v69
	v_exp_f32_e32 v61, v61
	v_add_f32_e32 v31, 1.0, v31
	v_rcp_f32_e32 v64, v31
	v_add_f32_e32 v31, 1.0, v65
	v_rcp_f32_e32 v65, v31
	v_add_f32_e32 v31, 1.0, v60
	v_rcp_f32_e32 v190, v31
	v_add_f32_e32 v31, 1.0, v61
	v_rcp_f32_e32 v191, v31
	v_pk_mul_f32 v[60:61], v[62:63], v[64:65]
	ds_read_b128 v[56:59], v164 offset:61440
	ds_read_b128 v[226:229], v164 offset:61456
	ds_read_b128 v[200:203], v164 offset:62208
	ds_read_b128 v[212:215], v164 offset:62224
	v_pk_mul_f32 v[62:63], v[68:69], v[190:191]
	v_lshlrev_b32_e32 v68, 16, v67
	v_and_b32_e32 v69, 0xffff0000, v67
	v_pk_fma_f32 v[68:69], v[76:77], v[68:69], 0 op_sel_hi:[1,1,0]
	v_lshlrev_b32_e32 v76, 16, v189
	v_and_b32_e32 v77, 0xffff0000, v189
	v_pk_fma_f32 v[68:69], v[198:199], v[76:77], v[68:69]
	v_lshlrev_b32_e32 v76, 16, v205
	v_and_b32_e32 v77, 0xffff0000, v205
	v_pk_fma_f32 v[68:69], v[210:211], v[76:77], v[68:69]
	v_lshlrev_b32_e32 v76, 16, v217
	v_and_b32_e32 v77, 0xffff0000, v217
	v_pk_fma_f32 v[68:69], v[222:223], v[76:77], v[68:69]
	v_lshlrev_b32_e32 v198, 16, v66
	v_mul_f32_e32 v31, 0xbfb8aa3b, v68
	v_exp_f32_e32 v31, v31
	v_mul_f32_e32 v67, 0xbfb8aa3b, v69
	v_exp_f32_e32 v67, v67
	v_and_b32_e32 v199, 0xffff0000, v66
	v_add_f32_e32 v31, 1.0, v31
	v_rcp_f32_e32 v190, v31
	v_add_f32_e32 v31, 1.0, v67
	v_pk_fma_f32 v[66:67], v[74:75], v[198:199], 0 op_sel_hi:[1,1,0]
	v_lshlrev_b32_e32 v74, 16, v188
	v_and_b32_e32 v75, 0xffff0000, v188
	v_pk_fma_f32 v[66:67], v[196:197], v[74:75], v[66:67]
	v_lshlrev_b32_e32 v74, 16, v204
	v_and_b32_e32 v75, 0xffff0000, v204
	v_lshlrev_b32_e32 v188, 16, v39
	v_and_b32_e32 v189, 0xffff0000, v39
	v_pk_fma_f32 v[66:67], v[208:209], v[74:75], v[66:67]
	v_lshlrev_b32_e32 v74, 16, v216
	v_and_b32_e32 v75, 0xffff0000, v216
	v_pk_fma_f32 v[72:73], v[72:73], v[188:189], 0 op_sel_hi:[1,1,0]
	v_lshlrev_b32_e32 v188, 16, v47
	v_and_b32_e32 v189, 0xffff0000, v47
	v_pk_fma_f32 v[66:67], v[220:221], v[74:75], v[66:67]
	v_pk_fma_f32 v[72:73], v[194:195], v[188:189], v[72:73]
	v_lshlrev_b32_e32 v188, 16, v51
	v_and_b32_e32 v189, 0xffff0000, v51
	v_rcp_f32_e32 v191, v31
	v_mul_f32_e32 v31, 0xbfb8aa3b, v66
	s_waitcnt lgkmcnt(2)
	v_pk_fma_f32 v[72:73], v[228:229], v[188:189], v[72:73]
	v_lshlrev_b32_e32 v188, 16, v55
	v_and_b32_e32 v189, 0xffff0000, v55
	v_exp_f32_e32 v31, v31
	v_mul_f32_e32 v74, 0xbfb8aa3b, v67
	s_waitcnt lgkmcnt(0)
	v_pk_fma_f32 v[72:73], v[214:215], v[188:189], v[72:73]
	v_exp_f32_e32 v75, v74
	v_mul_f32_e32 v39, 0xbfb8aa3b, v72
	v_exp_f32_e32 v39, v39
	v_mul_f32_e32 v47, 0xbfb8aa3b, v73
	v_exp_f32_e32 v47, v47
	v_add_f32_e32 v31, 1.0, v31
	v_rcp_f32_e32 v74, v31
	v_add_f32_e32 v31, 1.0, v75
	v_rcp_f32_e32 v75, v31
	v_add_f32_e32 v31, 1.0, v39
	v_rcp_f32_e32 v188, v31
	v_add_f32_e32 v31, 1.0, v47
	v_rcp_f32_e32 v189, v31
	v_and_b32_e32 v47, 0xffff0000, v50
	v_and_b32_e32 v55, 0xffff0000, v37
	v_pk_mul_f32 v[66:67], v[66:67], v[74:75]
	v_pk_mul_f32 v[72:73], v[72:73], v[188:189]
	v_lshlrev_b32_e32 v188, 16, v38
	v_and_b32_e32 v189, 0xffff0000, v38
	v_pk_fma_f32 v[38:39], v[70:71], v[188:189], 0 op_sel_hi:[1,1,0]
	v_lshlrev_b32_e32 v70, 16, v46
	v_and_b32_e32 v71, 0xffff0000, v46
	v_pk_fma_f32 v[38:39], v[192:193], v[70:71], v[38:39]
	v_lshlrev_b32_e32 v46, 16, v50
	v_pk_fma_f32 v[38:39], v[226:227], v[46:47], v[38:39]
	v_lshlrev_b32_e32 v46, 16, v54
	v_and_b32_e32 v47, 0xffff0000, v54
	v_pk_fma_f32 v[38:39], v[212:213], v[46:47], v[38:39]
	v_lshlrev_b32_e32 v54, 16, v37
	v_mul_f32_e32 v31, 0xbfb8aa3b, v38
	v_exp_f32_e32 v31, v31
	v_mul_f32_e32 v46, 0xbfb8aa3b, v39
	v_exp_f32_e32 v51, v46
	v_pk_fma_f32 v[34:35], v[34:35], v[54:55], 0 op_sel_hi:[1,1,0]
	v_lshlrev_b32_e32 v54, 16, v45
	v_and_b32_e32 v55, 0xffff0000, v45
	v_pk_fma_f32 v[34:35], v[42:43], v[54:55], v[34:35]
	v_lshlrev_b32_e32 v42, 16, v49
	v_and_b32_e32 v43, 0xffff0000, v49
	v_add_f32_e32 v31, 1.0, v31
	v_pk_fma_f32 v[34:35], v[58:59], v[42:43], v[34:35]
	v_lshlrev_b32_e32 v42, 16, v53
	v_and_b32_e32 v43, 0xffff0000, v53
	v_rcp_f32_e32 v50, v31
	v_add_f32_e32 v31, 1.0, v51
	v_pk_fma_f32 v[34:35], v[202:203], v[42:43], v[34:35]
	v_rcp_f32_e32 v51, v31
	v_mul_f32_e32 v31, 0xbfb8aa3b, v34
	v_exp_f32_e32 v31, v31
	v_mul_f32_e32 v37, 0xbfb8aa3b, v35
	v_exp_f32_e32 v37, v37
	v_pk_mul_f32 v[38:39], v[38:39], v[50:51]
	v_add_f32_e32 v31, 1.0, v31
; #define LAS __attribute__((address_space(3)))
; __device__ __forceinline__ unsigned pk2(float lo, float hi) { return pg8::cvt_pk_bf16_v(lo, hi); }
; __device__ __forceinline__ float siluf(float x) { return x * __builtin_amdgcn_rcpf(1.0f + __expf(-x)); }
; __device__ __forceinline__ void gdn_prep_all(const Params& P, LAS unsigned char* lds, int tid, int lane, int wave, int G) {
;     ...
;                 for (int j = 0; j < 4; ++j) {
;                     float rw[16];
;                     { const LAS v4u* rp = (const LAS v4u*)(hb + RAW_OFF + (t + j) * 384 + (p * 64 + 16 * cg) * 2);
;                       float f0[8], f1[8]; unpack8(rp[0], f0); unpack8(rp[1], f1);
; #pragma unroll
;                       for (int i = 0; i < 8; ++i) { rw[i] = f0[i]; rw[8 + i] = f1[i]; } }
;                     const LAS float* cwj = (const LAS float*)(hb + CW_OFF) + j * 192 + p * 64 + 16 * cg;
; #pragma unroll
;                     for (int i4 = 0; i4 < 4; ++i4) { const f32x4 w = ((const LAS f32x4*)cwj)[i4];
;                         acc[4 * i4] += rw[4 * i4] * w[0]; acc[4 * i4 + 1] += rw[4 * i4 + 1] * w[1]; acc[4 * i4 + 2] += rw[4 * i4 + 2] * w[2]; acc[4 * i4 + 3] += rw[4 * i4 + 3] * w[3]; }
;                 }
;                 float ss = 0.f;
; #pragma unroll
;                 for (int i = 0; i < 16; ++i) { acc[i] = siluf(acc[i]); ss += acc[i] * acc[i]; }
;                 ss += __shfl_xor(ss, 1); ss += __shfl_xor(ss, 2);
;                 float scale = 1.f;
;                 if (p == 0) scale = 0.125f * __builtin_amdgcn_rsqf(ss + 1e-6f); else if (p == 1) scale = __builtin_amdgcn_rsqf(ss + 1e-6f);
;                 if (t >= I.L) scale = 0.f;
;                 v4u o0, o1;
;                 o0.x = pk2(acc[0] * scale, acc[1] * scale); o0.y = pk2(acc[2] * scale, acc[3] * scale); o0.z = pk2(acc[4] * scale, acc[5] * scale); o0.w = pk2(acc[6] * scale, acc[7] * scale);
;                 o1.x = pk2(acc[8] * scale, acc[9] * scale); o1.y = pk2(acc[10] * scale, acc[11] * scale); o1.z = pk2(acc[12] * scale, acc[13] * scale); o1.w = pk2(acc[14] * scale, acc[15] * scale);
;                 LAS v4u* dst = (LAS v4u*)(hb + p * 9216 + t * 144 + cg * 32);
;                 dst[0] = o0; dst[1] = o1;
	v_lshlrev_b32_e32 v50, 16, v36
	v_and_b32_e32 v51, 0xffff0000, v36
	v_rcp_f32_e32 v42, v31
	v_add_f32_e32 v31, 1.0, v37
	v_pk_fma_f32 v[32:33], v[32:33], v[50:51], 0 op_sel_hi:[1,1,0]
	v_lshlrev_b32_e32 v36, 16, v44
	v_and_b32_e32 v37, 0xffff0000, v44
	v_pk_fma_f32 v[32:33], v[40:41], v[36:37], v[32:33]
	v_lshlrev_b32_e32 v36, 16, v48
	v_and_b32_e32 v37, 0xffff0000, v48
	v_pk_fma_f32 v[32:33], v[56:57], v[36:37], v[32:33]
	v_lshlrev_b32_e32 v36, 16, v52
	v_and_b32_e32 v37, 0xffff0000, v52
	v_pk_fma_f32 v[32:33], v[200:201], v[36:37], v[32:33]
	v_rcp_f32_e32 v43, v31
	v_mul_f32_e32 v36, 0xbfb8aa3b, v32
	v_exp_f32_e32 v36, v36
	v_mul_f32_e32 v37, 0xbfb8aa3b, v33
	v_exp_f32_e32 v37, v37
	v_pk_mul_f32 v[34:35], v[34:35], v[42:43]
	v_add_f32_e32 v31, 1.0, v36
	v_rcp_f32_e32 v36, v31
	v_add_f32_e32 v31, 1.0, v37
	v_rcp_f32_e32 v37, v31
	v_pk_mul_f32 v[42:43], v[34:35], v[34:35]
	v_pk_mul_f32 v[40:41], v[38:39], v[38:39]
	v_pk_mul_f32 v[46:47], v[72:73], v[72:73]
	v_pk_mul_f32 v[32:33], v[32:33], v[36:37]
	v_pk_mul_f32 v[74:75], v[66:67], v[66:67]
	v_pk_mul_f32 v[36:37], v[32:33], v[32:33]
	v_pk_mul_f32 v[68:69], v[68:69], v[190:191]
	v_add_f32_e32 v31, v36, v37
	v_add_f32_e32 v31, v42, v31
	v_add_f32_e32 v31, v43, v31
	v_add_f32_e32 v31, v40, v31
	v_add_f32_e32 v31, v41, v31
	v_add_f32_e32 v31, v46, v31
	v_add_f32_e32 v31, v47, v31
	v_add_f32_e32 v31, v74, v31
	v_pk_mul_f32 v[190:191], v[68:69], v[68:69]
	v_add_f32_e32 v31, v75, v31
	v_add_f32_e32 v31, v190, v31
	v_pk_mul_f32 v[76:77], v[62:63], v[62:63]
	v_add_f32_e32 v31, v191, v31
	v_add_f32_e32 v31, v76, v31
	v_pk_mul_f32 v[64:65], v[60:61], v[60:61]
	v_add_f32_e32 v31, v77, v31
	v_add_f32_e32 v31, v64, v31
	v_add_f32_e32 v31, v65, v31
	s_nop 1
	v_add_f32_dpp v31, v31, v31 quad_perm:[1,0,3,2] row_mask:0xf bank_mask:0xf
	s_nop 1
	v_add_f32_dpp v31, v31, v31 quad_perm:[2,3,0,1] row_mask:0xf bank_mask:0xf
	v_add_f32_e32 v31, 0x358637bd, v31
	v_rsq_f32_e32 v31, v31
	s_nop 0
	v_cndmask_b32_e32 v40, 0, v31, vcc
	v_pk_mul_f32 v[32:33], v[32:33], v[40:41] op_sel_hi:[1,0]
	v_pk_mul_f32 v[34:35], v[34:35], v[40:41] op_sel_hi:[1,0]
	v_cvt_pk_bf16_f32 v32, v32, v33
	v_cvt_pk_bf16_f32 v33, v34, v35
	v_pk_mul_f32 v[34:35], v[38:39], v[40:41] op_sel_hi:[1,0]
	v_pk_mul_f32 v[36:37], v[72:73], v[40:41] op_sel_hi:[1,0]
	v_cvt_pk_bf16_f32 v34, v34, v35
	v_cvt_pk_bf16_f32 v35, v36, v37
	v_pk_mul_f32 v[36:37], v[66:67], v[40:41] op_sel_hi:[1,0]
	v_pk_mul_f32 v[38:39], v[68:69], v[40:41] op_sel_hi:[1,0]
	v_cvt_pk_bf16_f32 v36, v36, v37
	v_cvt_pk_bf16_f32 v37, v38, v39
	v_pk_mul_f32 v[38:39], v[62:63], v[40:41] op_sel_hi:[1,0]
	v_pk_mul_f32 v[40:41], v[60:61], v[40:41] op_sel_hi:[1,0]
	v_cvt_pk_bf16_f32 v38, v38, v39
	v_cvt_pk_bf16_f32 v39, v40, v41
	ds_write_b128 v165, v[32:35] offset:9216
	ds_write_b128 v165, v[36:39] offset:9232
	ds_read_b128 v[64:67], v164 offset:60160
	ds_read_b128 v[188:191], v164 offset:60176
	ds_read_b128 v[68:71], v164 offset:60192
	ds_read_b128 v[36:39], v164 offset:60208
	ds_read_b128 v[192:195], v163 offset:27904
	ds_read_b128 v[48:51], v163 offset:27920
	ds_read_b128 v[32:35], v164 offset:62512
	ds_read_b128 v[72:75], v164 offset:62496
	ds_read_b128 v[40:43], v164 offset:61744
	ds_read_b128 v[196:199], v164 offset:61728
	ds_read_b128 v[44:47], v164 offset:60976
	ds_read_b128 v[200:203], v164 offset:60960
	ds_read_b128 v[60:63], v163 offset:29072
	ds_read_b128 v[204:207], v163 offset:29056
	ds_read_b128 v[56:59], v163 offset:28688
	ds_read_b128 v[208:211], v163 offset:28672
	ds_read_b128 v[52:55], v163 offset:28304
	ds_read_b128 v[212:215], v163 offset:28288
	ds_read_b128 v[216:219], v164 offset:62480
	ds_read_b128 v[220:223], v164 offset:62464
	ds_read_b128 v[224:227], v164 offset:61712
	ds_read_b128 v[228:231], v164 offset:61696
	ds_read_b128 v[232:235], v164 offset:60944
	ds_read_b128 v[236:239], v164 offset:60928
	s_waitcnt lgkmcnt(14)
	v_lshlrev_b32_e32 v76, 16, v192
	v_and_b32_e32 v77, 0xffff0000, v192
	v_pk_fma_f32 v[64:65], v[64:65], v[76:77], 0 op_sel_hi:[1,1,0]
	s_waitcnt lgkmcnt(6)
	v_lshlrev_b32_e32 v76, 16, v212
	v_and_b32_e32 v77, 0xffff0000, v212
	s_waitcnt lgkmcnt(0)
	v_pk_fma_f32 v[64:65], v[236:237], v[76:77], v[64:65]
	v_lshlrev_b32_e32 v76, 16, v208
	v_and_b32_e32 v77, 0xffff0000, v208
	v_pk_fma_f32 v[64:65], v[228:229], v[76:77], v[64:65]
	v_lshlrev_b32_e32 v76, 16, v204
	v_and_b32_e32 v77, 0xffff0000, v204
	v_pk_fma_f32 v[64:65], v[220:221], v[76:77], v[64:65]
	v_lshlrev_b32_e32 v192, 16, v193
	v_mul_f32_e32 v31, 0xbfb8aa3b, v65
	v_exp_f32_e32 v31, v31
	v_mul_f32_e32 v76, 0xbfb8aa3b, v64
	v_and_b32_e32 v193, 0xffff0000, v193
	v_exp_f32_e32 v77, v76
	v_lshlrev_b32_e32 v212, 16, v213
	v_and_b32_e32 v213, 0xffff0000, v213
	v_pk_fma_f32 v[66:67], v[66:67], v[192:193], 0 op_sel_hi:[1,1,0]
	v_lshlrev_b32_e32 v208, 16, v209
	v_and_b32_e32 v209, 0xffff0000, v209
	v_pk_fma_f32 v[66:67], v[238:239], v[212:213], v[66:67]
	v_lshlrev_b32_e32 v204, 16, v205
	v_and_b32_e32 v205, 0xffff0000, v205
	v_pk_fma_f32 v[66:67], v[230:231], v[208:209], v[66:67]
	v_add_f32_e32 v31, 1.0, v31
	v_pk_fma_f32 v[66:67], v[222:223], v[204:205], v[66:67]
	v_rcp_f32_e32 v221, v31
	v_add_f32_e32 v31, 1.0, v77
	v_mul_f32_e32 v77, 0xbfb8aa3b, v67
	v_exp_f32_e32 v77, v77
	v_mul_f32_e32 v187, 0xbfb8aa3b, v66
	v_exp_f32_e32 v187, v187
	v_rcp_f32_e32 v220, v31
	v_add_f32_e32 v31, 1.0, v77
	v_rcp_f32_e32 v193, v31
	v_add_f32_e32 v31, 1.0, v187
	v_rcp_f32_e32 v192, v31
	v_cndmask_b32_e64 v76, 0, 1.0, vcc
	v_pk_mul_f32 v[64:65], v[64:65], v[220:221]
	v_lshlrev_b32_e32 v204, 16, v211
	v_pk_mul_f32 v[66:67], v[66:67], v[192:193]
	v_lshlrev_b32_e32 v192, 16, v194
	v_and_b32_e32 v193, 0xffff0000, v194
; #define LAS __attribute__((address_space(3)))
; __device__ __forceinline__ unsigned pk2(float lo, float hi) { return pg8::cvt_pk_bf16_v(lo, hi); }
; __device__ __forceinline__ float siluf(float x) { return x * __builtin_amdgcn_rcpf(1.0f + __expf(-x)); }
; __device__ __forceinline__ void gdn_prep_all(const Params& P, LAS unsigned char* lds, int tid, int lane, int wave, int G) {
;     ...
;                 for (int j = 0; j < 4; ++j) {
;                     float rw[16];
;                     { const LAS v4u* rp = (const LAS v4u*)(hb + RAW_OFF + (t + j) * 384 + (p * 64 + 16 * cg) * 2);
;                       float f0[8], f1[8]; unpack8(rp[0], f0); unpack8(rp[1], f1);
; #pragma unroll
;                       for (int i = 0; i < 8; ++i) { rw[i] = f0[i]; rw[8 + i] = f1[i]; } }
;                     const LAS float* cwj = (const LAS float*)(hb + CW_OFF) + j * 192 + p * 64 + 16 * cg;
; #pragma unroll
;                     for (int i4 = 0; i4 < 4; ++i4) { const f32x4 w = ((const LAS f32x4*)cwj)[i4];
;                         acc[4 * i4] += rw[4 * i4] * w[0]; acc[4 * i4 + 1] += rw[4 * i4 + 1] * w[1]; acc[4 * i4 + 2] += rw[4 * i4 + 2] * w[2]; acc[4 * i4 + 3] += rw[4 * i4 + 3] * w[3]; }
;                 }
;                 float ss = 0.f;
; #pragma unroll
;                 for (int i = 0; i < 16; ++i) { acc[i] = siluf(acc[i]); ss += acc[i] * acc[i]; }
;                 ss += __shfl_xor(ss, 1); ss += __shfl_xor(ss, 2);
;                 float scale = 1.f;
;                 if (p == 0) scale = 0.125f * __builtin_amdgcn_rsqf(ss + 1e-6f); else if (p == 1) scale = __builtin_amdgcn_rsqf(ss + 1e-6f);
;                 if (t >= I.L) scale = 0.f;
;                 v4u o0, o1;
;                 o0.x = pk2(acc[0] * scale, acc[1] * scale); o0.y = pk2(acc[2] * scale, acc[3] * scale); o0.z = pk2(acc[4] * scale, acc[5] * scale); o0.w = pk2(acc[6] * scale, acc[7] * scale);
;                 o1.x = pk2(acc[8] * scale, acc[9] * scale); o1.y = pk2(acc[10] * scale, acc[11] * scale); o1.z = pk2(acc[12] * scale, acc[13] * scale); o1.w = pk2(acc[14] * scale, acc[15] * scale);
;                 LAS v4u* dst = (LAS v4u*)(hb + p * 9216 + t * 144 + cg * 32);
;                 dst[0] = o0; dst[1] = o1;
;             }
;         }
;         if (item + G < NCU * 4) GDN_PREFETCH(item + G);
	v_pk_fma_f32 v[188:189], v[188:189], v[192:193], 0 op_sel_hi:[1,1,0]
	v_lshlrev_b32_e32 v192, 16, v214
	v_and_b32_e32 v193, 0xffff0000, v214
	v_pk_fma_f32 v[188:189], v[232:233], v[192:193], v[188:189]
	v_lshlrev_b32_e32 v192, 16, v210
	v_and_b32_e32 v193, 0xffff0000, v210
	v_pk_fma_f32 v[188:189], v[224:225], v[192:193], v[188:189]
	v_lshlrev_b32_e32 v192, 16, v206
	v_and_b32_e32 v193, 0xffff0000, v206
	v_pk_fma_f32 v[188:189], v[216:217], v[192:193], v[188:189]
	v_pk_mul_f32 v[64:65], v[76:77], v[64:65] op_sel_hi:[0,1]
	v_mul_f32_e32 v31, 0xbfb8aa3b, v189
	v_lshlrev_b32_e32 v194, 16, v195
	v_and_b32_e32 v195, 0xffff0000, v195
	v_cvt_pk_bf16_f32 v64, v64, v65
	v_exp_f32_e32 v31, v31
	v_mul_f32_e32 v65, 0xbfb8aa3b, v188
	v_lshlrev_b32_e32 v192, 16, v207
	v_and_b32_e32 v193, 0xffff0000, v207
	v_lshlrev_b32_e32 v206, 16, v215
	v_and_b32_e32 v207, 0xffff0000, v215
	v_pk_fma_f32 v[190:191], v[190:191], v[194:195], 0 op_sel_hi:[1,1,0]
	v_pk_mul_f32 v[66:67], v[76:77], v[66:67] op_sel_hi:[0,1]
	v_exp_f32_e32 v77, v65
	v_and_b32_e32 v205, 0xffff0000, v211
	v_pk_fma_f32 v[190:191], v[234:235], v[206:207], v[190:191]
	v_cvt_pk_bf16_f32 v65, v66, v67
	v_pk_fma_f32 v[190:191], v[226:227], v[204:205], v[190:191]
	v_add_f32_e32 v31, 1.0, v31
	v_pk_fma_f32 v[190:191], v[218:219], v[192:193], v[190:191]
	v_rcp_f32_e32 v67, v31
	v_mul_f32_e32 v66, 0xbfb8aa3b, v191
	v_add_f32_e32 v31, 1.0, v77
	v_exp_f32_e32 v77, v66
	v_mul_f32_e32 v66, 0xbfb8aa3b, v190
	v_exp_f32_e32 v187, v66
	v_rcp_f32_e32 v66, v31
	v_add_f32_e32 v31, 1.0, v77
	v_rcp_f32_e32 v193, v31
	v_add_f32_e32 v31, 1.0, v187
	v_rcp_f32_e32 v192, v31
	v_pk_mul_f32 v[66:67], v[188:189], v[66:67]
	s_and_b64 vcc, exec, s[90:91]
	v_pk_mul_f32 v[66:67], v[76:77], v[66:67] op_sel_hi:[0,1]
	v_pk_mul_f32 v[188:189], v[190:191], v[192:193]
	v_lshlrev_b32_e32 v190, 16, v48
	v_and_b32_e32 v191, 0xffff0000, v48
	v_pk_fma_f32 v[68:69], v[68:69], v[190:191], 0 op_sel_hi:[1,1,0]
	v_lshlrev_b32_e32 v190, 16, v52
	v_and_b32_e32 v191, 0xffff0000, v52
	v_pk_fma_f32 v[68:69], v[200:201], v[190:191], v[68:69]
	v_lshlrev_b32_e32 v190, 16, v56
	v_and_b32_e32 v191, 0xffff0000, v56
	v_pk_fma_f32 v[68:69], v[196:197], v[190:191], v[68:69]
	v_lshlrev_b32_e32 v190, 16, v60
	v_and_b32_e32 v191, 0xffff0000, v60
	v_pk_fma_f32 v[68:69], v[72:73], v[190:191], v[68:69]
	v_lshlrev_b32_e32 v52, 16, v53
	v_mul_f32_e32 v31, 0xbfb8aa3b, v69
	v_exp_f32_e32 v31, v31
	v_mul_f32_e32 v48, 0xbfb8aa3b, v68
	v_exp_f32_e32 v48, v48
	v_and_b32_e32 v53, 0xffff0000, v53
	v_add_f32_e32 v31, 1.0, v31
	v_rcp_f32_e32 v73, v31
	v_add_f32_e32 v31, 1.0, v48
	v_lshlrev_b32_e32 v48, 16, v49
	v_and_b32_e32 v49, 0xffff0000, v49
	v_pk_fma_f32 v[48:49], v[70:71], v[48:49], 0 op_sel_hi:[1,1,0]
	v_lshlrev_b32_e32 v56, 16, v57
	v_and_b32_e32 v57, 0xffff0000, v57
	v_pk_fma_f32 v[48:49], v[202:203], v[52:53], v[48:49]
	v_lshlrev_b32_e32 v60, 16, v61
	v_and_b32_e32 v61, 0xffff0000, v61
	v_pk_fma_f32 v[48:49], v[198:199], v[56:57], v[48:49]
	v_rcp_f32_e32 v72, v31
	v_pk_fma_f32 v[52:53], v[74:75], v[60:61], v[48:49]
	v_pk_mul_f32 v[188:189], v[76:77], v[188:189] op_sel_hi:[0,1]
	v_mul_f32_e32 v48, 0xbfb8aa3b, v53
	v_exp_f32_e32 v48, v48
	v_mul_f32_e32 v49, 0xbfb8aa3b, v52
	v_exp_f32_e32 v49, v49
	v_cvt_pk_bf16_f32 v66, v66, v67
	v_add_f32_e32 v31, 1.0, v48
	v_rcp_f32_e32 v57, v31
	v_add_f32_e32 v31, 1.0, v49
	v_rcp_f32_e32 v56, v31
	v_pk_mul_f32 v[48:49], v[68:69], v[72:73]
	v_cvt_pk_bf16_f32 v67, v188, v189
	v_pk_mul_f32 v[48:49], v[76:77], v[48:49] op_sel_hi:[0,1]
	v_pk_mul_f32 v[52:53], v[52:53], v[56:57]
	v_lshlrev_b32_e32 v56, 16, v50
	v_and_b32_e32 v57, 0xffff0000, v50
	v_pk_fma_f32 v[36:37], v[36:37], v[56:57], 0 op_sel_hi:[1,1,0]
	v_lshlrev_b32_e32 v56, 16, v54
	v_and_b32_e32 v57, 0xffff0000, v54
	v_pk_fma_f32 v[36:37], v[44:45], v[56:57], v[36:37]
	v_lshlrev_b32_e32 v44, 16, v58
	v_and_b32_e32 v45, 0xffff0000, v58
	v_pk_fma_f32 v[36:37], v[40:41], v[44:45], v[36:37]
	v_lshlrev_b32_e32 v40, 16, v62
	v_and_b32_e32 v41, 0xffff0000, v62
	v_pk_fma_f32 v[32:33], v[32:33], v[40:41], v[36:37]
	v_pk_mul_f32 v[52:53], v[76:77], v[52:53] op_sel_hi:[0,1]
	v_mul_f32_e32 v31, 0xbfb8aa3b, v33
	v_exp_f32_e32 v31, v31
	v_mul_f32_e32 v36, 0xbfb8aa3b, v32
	v_lshlrev_b32_e32 v50, 16, v51
	v_and_b32_e32 v51, 0xffff0000, v51
	v_cvt_pk_bf16_f32 v48, v48, v49
	v_exp_f32_e32 v36, v36
	v_cvt_pk_bf16_f32 v49, v52, v53
	v_lshlrev_b32_e32 v52, 16, v55
	v_and_b32_e32 v53, 0xffff0000, v55
	v_pk_fma_f32 v[38:39], v[38:39], v[50:51], 0 op_sel_hi:[1,1,0]
	v_lshlrev_b32_e32 v44, 16, v59
	v_and_b32_e32 v45, 0xffff0000, v59
	v_pk_fma_f32 v[38:39], v[46:47], v[52:53], v[38:39]
	v_lshlrev_b32_e32 v40, 16, v63
	v_and_b32_e32 v41, 0xffff0000, v63
	v_pk_fma_f32 v[38:39], v[42:43], v[44:45], v[38:39]
	v_add_f32_e32 v31, 1.0, v31
	v_pk_fma_f32 v[34:35], v[34:35], v[40:41], v[38:39]
	v_rcp_f32_e32 v37, v31
	v_add_f32_e32 v31, 1.0, v36
	v_mul_f32_e32 v36, 0xbfb8aa3b, v35
	v_exp_f32_e32 v38, v36
	v_mul_f32_e32 v36, 0xbfb8aa3b, v34
	v_exp_f32_e32 v40, v36
	v_rcp_f32_e32 v36, v31
	v_add_f32_e32 v31, 1.0, v38
	v_rcp_f32_e32 v39, v31
	v_add_f32_e32 v31, 1.0, v40
	v_rcp_f32_e32 v38, v31
	v_pk_mul_f32 v[32:33], v[32:33], v[36:37]
	s_nop 0
	v_pk_mul_f32 v[32:33], v[76:77], v[32:33] op_sel_hi:[0,1]
	v_cvt_pk_bf16_f32 v50, v32, v33
	v_pk_mul_f32 v[32:33], v[34:35], v[38:39]
	s_nop 0
	v_pk_mul_f32 v[32:33], v[76:77], v[32:33] op_sel_hi:[0,1]
	v_cvt_pk_bf16_f32 v51, v32, v33
	ds_write_b128 v165, v[64:67] offset:18432
	ds_write_b128 v165, v[48:51] offset:18448
	s_cbranch_vccnz .LBB0_381
	s_ashr_i32 s51, s2, 2
	s_cmpk_gt_i32 s51, 0x3ff
	s_cselect_b64 s[58:59], -1, 0
	s_min_i32 s12, s51, 0x400
	s_and_b32 s61, s12, 0x7f
	s_cmpk_lt_i32 s51, 0x400
	s_mov_b64 s[14:15], -1
	s_cbranch_scc0 .LBB0_356
	s_ashr_i32 s60, s2, 9
	s_lshl_b32 s12, s60, 13
	s_lshl_b32 s13, s61, 6
	s_or_b32 s56, s13, s12
	s_mov_b64 s[14:15], 0
